# v65 plus sample retention item: the gate loads of its four output rows issued together (counted vmcnt(3)) instead of one load and vmcnt(0) per row
# baseline (speedup 1.0000x reference)
.LBB0_722:
	s_or_b64 exec, exec, s[10:11]
	s_or_b32 s5, s15, 0x2001
	s_or_b32 s4, s15, 0x2002
	s_waitcnt lgkmcnt(0)
	s_barrier
	s_and_saveexec_b64 s[2:3], vcc
	s_cbranch_execz .LBB0_724
	s_lshl_b32 s22, s94, 1
	v_readlane_b32 s6, v252, 47
	v_readlane_b32 s7, v252, 48
	s_add_u32 s18, s6, s22
	s_addc_u32 s19, s7, 0
	s_add_u32 s16, s13, s22
	s_addc_u32 s17, s14, 0
	s_mul_i32 s6, s5, 0x5800
	s_add_u32 s6, s0, s6
	s_addc_u32 s7, s1, 0
	s_mul_i32 s14, s12, 0x1c00
	s_add_u32 s12, s6, s22
	s_addc_u32 s13, s7, 0
	s_mul_i32 s10, s5, 0x1c00
	s_mul_i32 s5, s4, 0x5800
	s_add_u32 s5, s0, s5
	s_addc_u32 s6, s1, 0
	s_add_u32 s8, s5, s22
	s_addc_u32 s9, s6, 0
	s_mul_i32 s6, s4, 0x1c00
	s_mul_hi_u32 s4, s20, 0x5800
	s_add_u32 s5, s0, s21
	s_addc_u32 s21, s1, s4
	s_add_u32 s4, s5, s22
	s_addc_u32 s5, s21, 0
	v_or_b32_e32 v0, s94, v7
	s_mov_b64 s[22:23], s[88:89]
	s_mov_b64 s[24:25], s[80:81]
	s_mov_b64 s[26:27], s[82:83]
	s_mov_b64 s[28:29], s[86:87]
	s_mov_b64 s[30:31], s[90:91]
	s_mov_b32 s21, s85
	v_readlane_b32 s76, v252, 14
	v_lshlrev_b32_e32 v0, 2, v0
	v_readlane_b32 s88, v252, 26
	v_readlane_b32 s89, v252, 27
	v_mov_b32_e32 v17, v177
	v_lshl_add_u64 v[20:21], s[18:19], 0, v[16:17]
	s_mov_b32 s18, 0x3b800000
	s_mov_b32 s15, s95
	s_mov_b32 s11, s95
	global_load_dword v22, v0, s[88:89]
	ds_read_b128 v[10:13], v177 offset:4160
	ds_read_b128 v[0:3], v177 offset:4176
	ds_read_b128 v[24:27], v177 offset:4192
	ds_read_b128 v[4:7], v177 offset:4208
	ds_read_b128 v[28:31], v177 offset:4224
	ds_read_b128 v[32:35], v177 offset:4256
	s_waitcnt lgkmcnt(5)
	v_pk_add_f32 v[10:11], v[10:11], 0 op_sel_hi:[1,0]
	s_waitcnt lgkmcnt(4)
	v_pk_add_f32 v[0:1], v[0:1], 0 op_sel_hi:[1,0]
	s_waitcnt lgkmcnt(3)
	v_pk_add_f32 v[10:11], v[10:11], v[24:25]
	s_waitcnt lgkmcnt(2)
	v_pk_add_f32 v[0:1], v[0:1], v[4:5]
	s_waitcnt lgkmcnt(1)
	v_pk_add_f32 v[10:11], v[10:11], v[28:29]
	s_mov_b32 s7, s95
	s_waitcnt lgkmcnt(0)
	v_pk_add_f32 v[10:11], v[10:11], v[32:33]
	v_readlane_b32 s80, v252, 18
	v_pk_mul_f32 v[10:11], v[10:11], s[18:19] op_sel_hi:[1,0]
	s_mov_b32 s19, 0x800000
	v_fma_f32 v11, -v10, v10, v11
	v_max_f32_e32 v11, 0, v11
	v_add_f32_e32 v11, 0x358637bd, v11
	v_cmp_gt_f32_e32 vcc, s19, v11
	v_mul_f32_e32 v14, 0x4b800000, v11
	v_sub_f32_e32 v10, v9, v10
	v_cndmask_b32_e32 v11, v11, v14, vcc
	v_rsq_f32_e32 v11, v11
	v_readlane_b32 s81, v252, 19
	v_readlane_b32 s82, v252, 20
	v_readlane_b32 s83, v252, 21
	v_mul_f32_e32 v14, 0x45800000, v11
	v_cndmask_b32_e32 v11, v11, v14, vcc
	v_mul_f32_e32 v10, v10, v11
	v_readlane_b32 s84, v252, 22
	v_readlane_b32 s85, v252, 23
	v_readlane_b32 s86, v252, 24
	v_readlane_b32 s87, v252, 25
	v_readlane_b32 s90, v252, 28
	v_readlane_b32 s91, v252, 29
	s_mov_b32 s85, s21
	s_mov_b64 s[90:91], s[30:31]
	s_mov_b64 s[86:87], s[28:29]
	s_movk_i32 s84, 0x100
	s_mov_b64 s[82:83], s[26:27]
	s_mov_b64 s[80:81], s[24:25]
	s_mov_b64 s[88:89], s[22:23]
	v_readlane_b32 s77, v252, 15
	v_readlane_b32 s78, v252, 16
	v_readlane_b32 s79, v252, 17
	s_waitcnt vmcnt(0)
	v_mul_f32_e32 v14, v22, v10
	v_lshl_add_u64 v[10:11], s[16:17], 0, v[16:17]
	s_movk_i32 s16, 0x2000
	v_add_co_u32_e32 v10, vcc, s16, v10
	s_nop 1
	v_addc_co_u32_e32 v11, vcc, 0, v11, vcc
	v_lshl_add_u64 v[230:231], s[12:13], 0, v[16:17]
	v_lshl_add_u64 v[232:233], s[8:9], 0, v[16:17]
	v_lshl_add_u64 v[234:235], s[4:5], 0, v[16:17]
	v_add_co_u32_e32 v230, vcc, s16, v230
	v_addc_co_u32_e32 v231, vcc, 0, v231, vcc
	v_add_co_u32_e32 v232, vcc, s16, v232
	v_addc_co_u32_e32 v233, vcc, 0, v233, vcc
	v_add_co_u32_e32 v234, vcc, s16, v234
	v_addc_co_u32_e32 v235, vcc, 0, v235, vcc
	global_load_ushort v10, v[10:11], off
	global_load_ushort v236, v[230:231], off
	global_load_ushort v237, v[232:233], off
	global_load_ushort v238, v[234:235], off
	s_waitcnt vmcnt(3)
	v_lshlrev_b32_e32 v10, 16, v10
	v_mul_f32_e32 v11, 0xbfb8aa3b, v10
	v_exp_f32_e32 v11, v11
	s_nop 0
	v_add_f32_e32 v11, 1.0, v11
	v_rcp_f32_e32 v11, v11
	s_nop 0
	v_mul_f32_e32 v10, v11, v10
	v_mul_f32_e32 v10, v10, v14
	v_cvt_pk_bf16_f32 v14, v10, s0
	v_lshl_add_u64 v[10:11], v[20:21], 0, s[14:15]
	global_store_short v[10:11], v14, off
	v_pk_add_f32 v[10:11], v[12:13], 0 op_sel_hi:[1,0]
	s_nop 0
	v_pk_add_f32 v[10:11], v[10:11], v[26:27]
	s_nop 0
	v_pk_add_f32 v[10:11], v[10:11], v[30:31]
	s_nop 0
	v_pk_add_f32 v[10:11], v[10:11], v[34:35]
	s_nop 0
	v_pk_mul_f32 v[12:13], v[10:11], s[18:19] op_sel_hi:[1,0]
	v_pk_fma_f32 v[8:9], v[10:11], s[18:19], v[8:9] op_sel_hi:[1,0,1] neg_lo:[1,0,0] neg_hi:[1,0,0]
	v_fma_f32 v12, -v12, v12, v13
	v_max_f32_e32 v12, 0, v12
	v_add_f32_e32 v12, 0x358637bd, v12
	v_cmp_gt_f32_e32 vcc, s19, v12
	v_mul_f32_e32 v13, 0x4b800000, v12
	s_nop 0
	v_cndmask_b32_e32 v12, v12, v13, vcc
	v_rsq_f32_e32 v12, v12
	s_nop 0
	v_mul_f32_e32 v13, 0x45800000, v12
	v_cndmask_b32_e32 v12, v12, v13, vcc
	v_mul_f32_e32 v8, v8, v12
	v_mul_f32_e32 v10, v22, v8
	v_lshl_add_u64 v[8:9], s[12:13], 0, v[16:17]
	v_add_co_u32_e32 v8, vcc, s16, v8
	ds_read_b128 v[12:15], v177 offset:4272
	s_nop 0
	v_addc_co_u32_e32 v9, vcc, 0, v9, vcc
	s_waitcnt vmcnt(3)
	v_mov_b32_e32 v8, v236
	v_lshlrev_b32_e32 v8, 16, v8
	v_mul_f32_e32 v9, 0xbfb8aa3b, v8
	v_exp_f32_e32 v9, v9
	s_nop 0
	v_add_f32_e32 v9, 1.0, v9
	v_rcp_f32_e32 v9, v9
	s_nop 0
	v_mul_f32_e32 v8, v9, v8
	v_mul_f32_e32 v8, v8, v10
	v_cvt_pk_bf16_f32 v10, v8, s0
	v_lshl_add_u64 v[8:9], v[20:21], 0, s[10:11]
	global_store_short v[8:9], v10, off
	ds_read_b128 v[8:11], v177 offset:4240
	s_waitcnt lgkmcnt(0)
	v_pk_add_f32 v[0:1], v[0:1], v[8:9]
	s_nop 0
	v_pk_add_f32 v[0:1], v[0:1], v[12:13]
	s_nop 0
	v_pk_mul_f32 v[0:1], v[0:1], s[18:19] op_sel_hi:[1,0]
	s_nop 0
	v_fma_f32 v1, -v0, v0, v1
	v_max_f32_e32 v1, 0, v1
	v_add_f32_e32 v1, 0x358637bd, v1
	v_cmp_gt_f32_e32 vcc, s19, v1
	v_mul_f32_e32 v4, 0x4b800000, v1
	v_sub_f32_e32 v0, v19, v0
	v_cndmask_b32_e32 v1, v1, v4, vcc
	v_rsq_f32_e32 v1, v1
	s_nop 0
	v_mul_f32_e32 v4, 0x45800000, v1
	v_cndmask_b32_e32 v1, v1, v4, vcc
	v_lshl_add_u64 v[4:5], s[8:9], 0, v[16:17]
	v_add_co_u32_e32 v4, vcc, s16, v4
	v_mul_f32_e32 v0, v0, v1
	s_nop 0
	v_addc_co_u32_e32 v5, vcc, 0, v5, vcc
	v_mul_f32_e32 v0, v22, v0
	s_waitcnt vmcnt(3)
	v_mov_b32_e32 v1, v237
	v_lshlrev_b32_e32 v1, 16, v1
	v_mul_f32_e32 v4, 0xbfb8aa3b, v1
	v_exp_f32_e32 v4, v4
	s_nop 0
	v_add_f32_e32 v4, 1.0, v4
	v_rcp_f32_e32 v4, v4
	s_nop 0
	v_mul_f32_e32 v1, v4, v1
	v_mul_f32_e32 v0, v1, v0
	v_cvt_pk_bf16_f32 v4, v0, s0
	v_lshl_add_u64 v[0:1], v[20:21], 0, s[6:7]
	global_store_short v[0:1], v4, off
	v_pk_add_f32 v[0:1], v[2:3], 0 op_sel_hi:[1,0]
	s_nop 0
	v_pk_add_f32 v[0:1], v[0:1], v[6:7]
	s_nop 0
	v_pk_add_f32 v[0:1], v[0:1], v[10:11]
	s_nop 0
	v_pk_add_f32 v[0:1], v[0:1], v[14:15]
	s_nop 0
	v_pk_mul_f32 v[2:3], v[0:1], s[18:19] op_sel_hi:[1,0]
	v_pk_fma_f32 v[0:1], v[0:1], s[18:19], v[18:19] op_sel_hi:[1,0,1] neg_lo:[1,0,0] neg_hi:[1,0,0]
	v_fma_f32 v2, -v2, v2, v3
	v_max_f32_e32 v2, 0, v2
	v_add_f32_e32 v2, 0x358637bd, v2
	v_cmp_gt_f32_e32 vcc, s19, v2
	v_mul_f32_e32 v3, 0x4b800000, v2
	s_nop 0
	v_cndmask_b32_e32 v2, v2, v3, vcc
	v_rsq_f32_e32 v2, v2
	s_nop 0
	v_mul_f32_e32 v3, 0x45800000, v2
	v_cndmask_b32_e32 v2, v2, v3, vcc
	v_mul_f32_e32 v0, v0, v2
	v_mul_f32_e32 v2, v22, v0
	v_lshl_add_u64 v[0:1], s[4:5], 0, v[16:17]
	v_add_co_u32_e32 v0, vcc, 0x2000, v0
	s_nop 1
	v_addc_co_u32_e32 v1, vcc, 0, v1, vcc
	s_waitcnt vmcnt(3)
	v_mov_b32_e32 v0, v238
	v_lshlrev_b32_e32 v0, 16, v0
	v_mul_f32_e32 v1, 0xbfb8aa3b, v0
	v_exp_f32_e32 v1, v1
	s_nop 0
	v_add_f32_e32 v1, 1.0, v1
	v_rcp_f32_e32 v1, v1
	s_nop 0
	v_mul_f32_e32 v0, v1, v0
	v_mul_f32_e32 v0, v0, v2
	v_cvt_pk_bf16_f32 v2, v0, s0
	v_mad_u64_u32 v[0:1], s[4:5], s20, v228, v[20:21]
	global_store_short v[0:1], v2, off
